# in-proj GEMM loops peeled as well (six of eight GEMMs)
# speedup vs baseline: 1.0238x; 1.0008x over previous
; #define PG8_STAGE(bufoff, gbase, voff) do { _Pragma("unroll") for (int _i = 0; _i < 2; ++_i) \
;         __builtin_amdgcn_global_load_lds((const unsigned*)((const char*)(gbase) + (voff)[_i]), (PG8_LAS unsigned*)(lds + (bufoff) + ldsw + _i * 8192), 16, 0, 0); } while (0)
; #define PG8_LDA(dst, b, h) do { _Pragma("unroll") for (int m = 0; m < 4; ++m) _Pragma("unroll") for (int k = 0; k < 2; ++k) dst[m][k] = *(const PG8_LAS bf16x8*)(lds + PG8_SA(b, h) + aoff + m * 2048 + k * 1024); } while (0)
; #define PG8_LDB(dst, b, h) do { _Pragma("unroll") for (int n = 0; n < 2; ++n) _Pragma("unroll") for (int k = 0; k < 2; ++k) dst[n][k] = *(const PG8_LAS bf16x8*)(lds + PG8_SB(b, h) + boff + n * 2048 + k * 1024); } while (0)
; #define PG8_WAIT_V(n) asm volatile("s_waitcnt vmcnt(" #n ")" ::: "memory")
; #define PG8_BAR __builtin_amdgcn_s_barrier()
; template <class Epi, class Sched, bool ALIGN_EPI = false, bool SP2 = false>
; __device__ __forceinline__ void gemm_phase(PG8_LAS unsigned char* lds, const Gemm g, const Sched& S, const Epi& E) {
;     ...
;         const char* nA = has_next ? (const char*)g.A + (size_t)nxt.pm * tstepA + (size_t)(nxt.k0 >> 6) * kstepA + (nxt.qa > 0 ? hstepA : (size_t)0) : cA; const char* nB = has_next ? (const char*)g.Bt + (size_t)nxt.pn * tstepB + (size_t)nxt.k0 * 2 + (nxt.qb > 0 ? hstepB : (size_t)0) : cB;
;         const bool whole = cur.qa < 0;
;         const int nt = cur.nt;
;         for (int t = 0; t < nt; t += 2) {
;             const bool last = (t == nt - 2);
;             const char* a1 = cA + (size_t)(t + 1) * kstepA;
;             const char* a2 = last ? nA : cA + (size_t)(t + 2) * kstepA; const char* b2 = last ? nB : cB + (size_t)(t + 2) * kstep;
;             const char* a3 = a2 + kstepA; const char* b3 = b2 + kstep;
;             if (last && has_next) S.a_ready(nxt);
;             if constexpr (SP2) {
;             PG8_LDB(B0, 0, 0); PG8_LDB(B1, 0, 1); PG8_SCHED; PG8_LDA(At, 0, 0); PG8_STAGE(PG8_SA(1, 1), a1 + hstepA, voffA);
;             PG8_WAIT_V(8); PG8_WAIT_L(0); PG8_BAR; PG8_MMA(0, 0, At, B0); if (whole) PG8_MMA(0, 1, At, B1); PG8_BAR; PG8_SCHED;
;             PG8_LDA(At, 0, 1); PG8_STAGE(PG8_SB(0, 0), b2, voffB); PG8_STAGE(PG8_SB(0, 1), b2 + hstepB, voffB); PG8_STAGE(PG8_SA(0, 0), a2, voffA);
;             PG8_WAIT_V(8); PG8_WAIT_L(0); PG8_BAR; if (whole) { PG8_MMA(1, 0, At, B0); PG8_MMA(1, 1, At, B1); } PG8_BAR; PG8_SCHED;
.LBB0_104:
	s_ashr_i32 s91, s90, 31
	s_lshl_b64 s[6:7], s[90:91], 19
	s_add_u32 s92, s30, s6
	s_addc_u32 s93, s31, s7
	s_and_b64 s[6:7], s[2:3], exec
	s_cselect_b32 s1, s93, s97
	s_cselect_b32 s9, s92, s96
	s_ashr_i32 s89, s88, 31
	s_lshl_b64 s[6:7], s[88:89], 19
	s_add_u32 s6, s8, s6
	s_addc_u32 s7, s52, s7
	s_and_b64 s[12:13], s[2:3], exec
	s_cselect_b32 s12, s7, s95
	s_cselect_b32 s13, s6, s94
	s_add_u32 s96, s96, 0x40080
	s_addc_u32 s97, s97, 0
	s_add_u32 s14, s94, 0x100
	s_addc_u32 s15, s95, 0
	s_mov_b32 s16, -2
	ds_read_b128 v[148:151], v161
	ds_read_b128 v[152:155], v161 offset:1024
	ds_read_b128 v[156:159], v161 offset:2048
	ds_read_b128 v[166:169], v161 offset:3072
	ds_read_b128 v[170:173], v162
	ds_read_b128 v[174:177], v162 offset:1024
	ds_read_b128 v[178:181], v162 offset:2048
	ds_read_b128 v[182:185], v162 offset:3072
	s_add_u32 s17, s96, 0xfffc0080
	s_addc_u32 s18, s97, -1
	s_cmp_eq_u32 s16, 12
	s_cselect_b32 vcc_hi, s1, s18
	s_cselect_b32 vcc_lo, s9, s17
	s_cselect_b32 s95, s12, s15
	s_cselect_b32 s94, s13, s14
	v_lshl_add_u64 v[218:219], s[96:97], 0, v[140:141]
	s_add_i32 m0, s51, 0xc000
	ds_read_b128 v[186:189], v163
	ds_read_b128 v[190:193], v163 offset:1024
	ds_read_b128 v[194:197], v163 offset:2048
	ds_read_b128 v[198:201], v163 offset:3072
	ds_read_b128 v[202:205], v163 offset:4096
	ds_read_b128 v[206:209], v163 offset:5120
	ds_read_b128 v[210:213], v163 offset:6144
	ds_read_b128 v[214:217], v163 offset:7168
	global_load_lds_dwordx4 v[218:219], off
	v_lshl_add_u64 v[218:219], s[96:97], 0, v[142:143]
	s_add_i32 m0, s51, 0xe000
	s_nop 0
	global_load_lds_dwordx4 v[218:219], off
	s_waitcnt vmcnt(16)
	s_waitcnt lgkmcnt(0)
	s_barrier
	s_setprio 1
	s_waitcnt lgkmcnt(0)
	v_mfma_f32_16x16x32_bf16 v[124:127], v[148:151], v[186:189], 0
	v_mfma_f32_16x16x32_bf16 v[120:123], v[156:159], v[186:189], 0
	v_mfma_f32_16x16x32_bf16 v[108:111], v[148:151], v[194:197], 0
	v_mfma_f32_16x16x32_bf16 v[104:107], v[156:159], v[194:197], 0
	v_mfma_f32_16x16x32_bf16 v[92:95], v[148:151], v[202:205], 0
	v_mfma_f32_16x16x32_bf16 v[88:91], v[156:159], v[202:205], 0
	v_mfma_f32_16x16x32_bf16 v[76:79], v[148:151], v[210:213], 0
	v_mfma_f32_16x16x32_bf16 v[72:75], v[156:159], v[210:213], 0
	v_mfma_f32_16x16x32_bf16 v[124:127], v[152:155], v[190:193], v[124:127]
	v_mfma_f32_16x16x32_bf16 v[120:123], v[166:169], v[190:193], v[120:123]
	v_mfma_f32_16x16x32_bf16 v[108:111], v[152:155], v[198:201], v[108:111]
	v_mfma_f32_16x16x32_bf16 v[104:107], v[166:169], v[198:201], v[104:107]
	v_mfma_f32_16x16x32_bf16 v[92:95], v[152:155], v[206:209], v[92:95]
	v_mfma_f32_16x16x32_bf16 v[88:91], v[166:169], v[206:209], v[88:91]
	v_mfma_f32_16x16x32_bf16 v[76:79], v[152:155], v[214:217], v[76:79]
	v_mfma_f32_16x16x32_bf16 v[72:75], v[166:169], v[214:217], v[72:75]
	s_setprio 0
	s_setprio 1
	v_mfma_f32_16x16x32_bf16 v[116:119], v[170:173], v[186:189], 0
	v_mfma_f32_16x16x32_bf16 v[112:115], v[178:181], v[186:189], 0
	v_mfma_f32_16x16x32_bf16 v[100:103], v[170:173], v[194:197], 0
	v_mfma_f32_16x16x32_bf16 v[96:99], v[178:181], v[194:197], 0
	v_mfma_f32_16x16x32_bf16 v[84:87], v[170:173], v[202:205], 0
	v_mfma_f32_16x16x32_bf16 v[80:83], v[178:181], v[202:205], 0
	v_mfma_f32_16x16x32_bf16 v[68:71], v[170:173], v[210:213], 0
	v_mfma_f32_16x16x32_bf16 v[64:67], v[178:181], v[210:213], 0
	v_mfma_f32_16x16x32_bf16 v[116:119], v[174:177], v[190:193], v[116:119]
	v_mfma_f32_16x16x32_bf16 v[112:115], v[182:185], v[190:193], v[112:115]
	v_mfma_f32_16x16x32_bf16 v[100:103], v[174:177], v[198:201], v[100:103]
	v_mfma_f32_16x16x32_bf16 v[96:99], v[182:185], v[198:201], v[96:99]
	v_mfma_f32_16x16x32_bf16 v[84:87], v[174:177], v[206:209], v[84:87]
	v_mfma_f32_16x16x32_bf16 v[80:83], v[182:185], v[206:209], v[80:83]
	v_mfma_f32_16x16x32_bf16 v[68:71], v[174:177], v[214:217], v[68:71]
	v_mfma_f32_16x16x32_bf16 v[64:67], v[182:185], v[214:217], v[64:67]
	s_setprio 0
	s_barrier
	s_add_i32 s17, s62, s53
	v_lshl_add_u64 v[218:219], s[94:95], 0, v[130:131]
	s_mov_b32 m0, s17
	ds_read_b128 v[186:189], v163 offset:16384
	ds_read_b128 v[190:193], v163 offset:17408
	ds_read_b128 v[194:197], v163 offset:18432
	ds_read_b128 v[198:201], v163 offset:19456
	ds_read_b128 v[202:205], v163 offset:20480
	ds_read_b128 v[206:209], v163 offset:21504
	ds_read_b128 v[210:213], v163 offset:22528
	ds_read_b128 v[214:217], v163 offset:23552
	global_load_lds_dwordx4 v[218:219], off
	s_add_i32 m0, s17, 0x2000
	s_add_u32 s18, s94, 0x40000
	v_lshl_add_u64 v[220:221], s[94:95], 0, v[134:135]
	s_addc_u32 s19, s95, 0
	s_add_i32 s17, s63, s53
	global_load_lds_dwordx4 v[220:221], off
	v_lshl_add_u64 v[222:223], s[18:19], 0, v[130:131]
	s_mov_b32 m0, s17
	v_lshl_add_u64 v[224:225], vcc, 0, v[132:133]
	global_load_lds_dwordx4 v[222:223], off
	v_lshl_add_u64 v[222:223], s[18:19], 0, v[134:135]
	s_add_i32 m0, s17, 0x2000
	s_nop 0
	global_load_lds_dwordx4 v[222:223], off
	v_lshl_add_u64 v[222:223], vcc, 0, v[128:129]
	s_mov_b32 m0, s51
	s_nop 0
	global_load_lds_dwordx4 v[222:223], off
	s_mov_b32 m0, s54
	s_nop 0
	global_load_lds_dwordx4 v[224:225], off
	s_waitcnt vmcnt(16)
	s_waitcnt lgkmcnt(0)
	s_barrier
; #define PG8_STAGE(bufoff, gbase, voff) do { _Pragma("unroll") for (int _i = 0; _i < 2; ++_i) \
;         __builtin_amdgcn_global_load_lds((const unsigned*)((const char*)(gbase) + (voff)[_i]), (PG8_LAS unsigned*)(lds + (bufoff) + ldsw + _i * 8192), 16, 0, 0); } while (0)
; #define PG8_LDA(dst, b, h) do { _Pragma("unroll") for (int m = 0; m < 4; ++m) _Pragma("unroll") for (int k = 0; k < 2; ++k) dst[m][k] = *(const PG8_LAS bf16x8*)(lds + PG8_SA(b, h) + aoff + m * 2048 + k * 1024); } while (0)
; #define PG8_LDB(dst, b, h) do { _Pragma("unroll") for (int n = 0; n < 2; ++n) _Pragma("unroll") for (int k = 0; k < 2; ++k) dst[n][k] = *(const PG8_LAS bf16x8*)(lds + PG8_SB(b, h) + boff + n * 2048 + k * 1024); } while (0)
; #define PG8_MMA(ai, bj, At, Bt) do { __builtin_amdgcn_s_setprio(1); _Pragma("unroll") for (int m = 0; m < 4; ++m) _Pragma("unroll") for (int n = 0; n < 2; ++n) _Pragma("unroll") for (int k = 0; k < 2; ++k) \
;         acc[ai][bj][m][n] = __builtin_amdgcn_mfma_f32_16x16x32_bf16(Bt[n][k], At[m][k], acc[ai][bj][m][n], 0, 0, 0); __builtin_amdgcn_s_setprio(0); } while (0)
; #define PG8_WAIT_V(n) asm volatile("s_waitcnt vmcnt(" #n ")" ::: "memory")
; #define PG8_WAIT_L(n) asm volatile("s_waitcnt lgkmcnt(" #n ")" ::: "memory")
; #define PG8_BAR __builtin_amdgcn_s_barrier()
; #define PG8_SCHED __builtin_amdgcn_sched_barrier(0)
; template <class Epi, class Sched, bool ALIGN_EPI = false, bool SP2 = false>
; __device__ __forceinline__ void gemm_phase(PG8_LAS unsigned char* lds, const Gemm g, const Sched& S, const Epi& E) {
;     ...
;             PG8_WAIT_V(8); PG8_WAIT_L(0); PG8_BAR; if (whole) { PG8_MMA(1, 0, At, B0); PG8_MMA(1, 1, At, B1); } PG8_BAR; PG8_SCHED;
;             PG8_LDB(B0, 1, 0); PG8_LDB(B1, 1, 1); PG8_SCHED; PG8_LDA(At, 1, 0); PG8_STAGE(PG8_SA(0, 1), a2 + hstepA, voffA);
;             PG8_WAIT_V(8); PG8_WAIT_L(0); PG8_BAR; PG8_MMA(0, 0, At, B0); if (whole) PG8_MMA(0, 1, At, B1); PG8_BAR; PG8_SCHED;
	s_setprio 1
	s_waitcnt lgkmcnt(0)
	v_mfma_f32_16x16x32_bf16 v[60:63], v[148:151], v[186:189], 0
	v_mfma_f32_16x16x32_bf16 v[56:59], v[156:159], v[186:189], 0
	v_mfma_f32_16x16x32_bf16 v[44:47], v[148:151], v[194:197], 0
	v_mfma_f32_16x16x32_bf16 v[40:43], v[156:159], v[194:197], 0
	v_mfma_f32_16x16x32_bf16 v[28:31], v[148:151], v[202:205], 0
	v_mfma_f32_16x16x32_bf16 v[24:27], v[156:159], v[202:205], 0
	v_mfma_f32_16x16x32_bf16 v[12:15], v[148:151], v[210:213], 0
	v_mfma_f32_16x16x32_bf16 v[8:11], v[156:159], v[210:213], 0
	v_mfma_f32_16x16x32_bf16 v[60:63], v[152:155], v[190:193], v[60:63]
	v_mfma_f32_16x16x32_bf16 v[56:59], v[166:169], v[190:193], v[56:59]
	v_mfma_f32_16x16x32_bf16 v[44:47], v[152:155], v[198:201], v[44:47]
	v_mfma_f32_16x16x32_bf16 v[40:43], v[166:169], v[198:201], v[40:43]
	v_mfma_f32_16x16x32_bf16 v[28:31], v[152:155], v[206:209], v[28:31]
	v_mfma_f32_16x16x32_bf16 v[24:27], v[166:169], v[206:209], v[24:27]
	v_mfma_f32_16x16x32_bf16 v[12:15], v[152:155], v[214:217], v[12:15]
	v_mfma_f32_16x16x32_bf16 v[8:11], v[166:169], v[214:217], v[8:11]
	s_setprio 0
	s_setprio 1
	v_mfma_f32_16x16x32_bf16 v[52:55], v[170:173], v[186:189], 0
	v_mfma_f32_16x16x32_bf16 v[48:51], v[178:181], v[186:189], 0
	v_mfma_f32_16x16x32_bf16 v[36:39], v[170:173], v[194:197], 0
	v_mfma_f32_16x16x32_bf16 v[32:35], v[178:181], v[194:197], 0
	v_mfma_f32_16x16x32_bf16 v[20:23], v[170:173], v[202:205], 0
	v_mfma_f32_16x16x32_bf16 v[16:19], v[178:181], v[202:205], 0
	v_mfma_f32_16x16x32_bf16 v[4:7], v[170:173], v[210:213], 0
	v_mfma_f32_16x16x32_bf16 v[0:3], v[178:181], v[210:213], 0
	v_mfma_f32_16x16x32_bf16 v[52:55], v[174:177], v[190:193], v[52:55]
	v_mfma_f32_16x16x32_bf16 v[48:51], v[182:185], v[190:193], v[48:51]
	v_mfma_f32_16x16x32_bf16 v[36:39], v[174:177], v[198:201], v[36:39]
	v_mfma_f32_16x16x32_bf16 v[32:35], v[182:185], v[198:201], v[32:35]
	v_mfma_f32_16x16x32_bf16 v[20:23], v[174:177], v[206:209], v[20:23]
	v_mfma_f32_16x16x32_bf16 v[16:19], v[182:185], v[206:209], v[16:19]
	v_mfma_f32_16x16x32_bf16 v[4:7], v[174:177], v[214:217], v[4:7]
	v_mfma_f32_16x16x32_bf16 v[0:3], v[182:185], v[214:217], v[0:3]
	s_setprio 0
	s_barrier
	s_add_i32 s17, 0, 0x18000
	v_add_u32_e32 v136, s17, v160
	s_add_i32 s20, 0, 0x1c000
	ds_read_b128 v[148:151], v136
	ds_read_b128 v[152:155], v136 offset:1024
	ds_read_b128 v[156:159], v136 offset:2048
	ds_read_b128 v[166:169], v136 offset:3072
	v_add_u32_e32 v136, s20, v160
	ds_read_b128 v[170:173], v136
	ds_read_b128 v[174:177], v136 offset:1024
	ds_read_b128 v[178:181], v136 offset:2048
	ds_read_b128 v[182:185], v136 offset:3072
	s_add_u32 s18, vcc_lo, 0x40000
	s_addc_u32 s19, vcc_hi, 0
	s_mov_b32 m0, s55
	v_lshl_add_u64 v[226:227], s[18:19], 0, v[128:129]
	ds_read_b128 v[186:189], v163 offset:32768
	ds_read_b128 v[190:193], v163 offset:33792
	ds_read_b128 v[194:197], v163 offset:34816
	ds_read_b128 v[198:201], v163 offset:35840
	ds_read_b128 v[202:205], v163 offset:36864
	ds_read_b128 v[206:209], v163 offset:37888
	ds_read_b128 v[210:213], v163 offset:38912
	ds_read_b128 v[214:217], v163 offset:39936
	global_load_lds_dwordx4 v[226:227], off
	v_lshl_add_u64 v[226:227], s[18:19], 0, v[132:133]
	s_mov_b32 m0, s56
	s_nop 0
	global_load_lds_dwordx4 v[226:227], off
	s_waitcnt vmcnt(8)
	s_waitcnt lgkmcnt(0)
	s_barrier
	s_setprio 1
	s_waitcnt lgkmcnt(0)
	v_mfma_f32_16x16x32_bf16 v[124:127], v[148:151], v[186:189], v[124:127]
	v_mfma_f32_16x16x32_bf16 v[120:123], v[156:159], v[186:189], v[120:123]
	v_mfma_f32_16x16x32_bf16 v[108:111], v[148:151], v[194:197], v[108:111]
	v_mfma_f32_16x16x32_bf16 v[104:107], v[156:159], v[194:197], v[104:107]
	v_mfma_f32_16x16x32_bf16 v[92:95], v[148:151], v[202:205], v[92:95]
	v_mfma_f32_16x16x32_bf16 v[88:91], v[156:159], v[202:205], v[88:91]
	v_mfma_f32_16x16x32_bf16 v[76:79], v[148:151], v[210:213], v[76:79]
	v_mfma_f32_16x16x32_bf16 v[72:75], v[156:159], v[210:213], v[72:75]
	v_mfma_f32_16x16x32_bf16 v[124:127], v[152:155], v[190:193], v[124:127]
	v_mfma_f32_16x16x32_bf16 v[120:123], v[166:169], v[190:193], v[120:123]
	v_mfma_f32_16x16x32_bf16 v[108:111], v[152:155], v[198:201], v[108:111]
	v_mfma_f32_16x16x32_bf16 v[104:107], v[166:169], v[198:201], v[104:107]
	v_mfma_f32_16x16x32_bf16 v[92:95], v[152:155], v[206:209], v[92:95]
	v_mfma_f32_16x16x32_bf16 v[88:91], v[166:169], v[206:209], v[88:91]
	v_mfma_f32_16x16x32_bf16 v[76:79], v[152:155], v[214:217], v[76:79]
	v_mfma_f32_16x16x32_bf16 v[72:75], v[166:169], v[214:217], v[72:75]
	s_setprio 0
	s_setprio 1
	v_mfma_f32_16x16x32_bf16 v[116:119], v[170:173], v[186:189], v[116:119]
	v_mfma_f32_16x16x32_bf16 v[112:115], v[178:181], v[186:189], v[112:115]
	v_mfma_f32_16x16x32_bf16 v[100:103], v[170:173], v[194:197], v[100:103]
	v_mfma_f32_16x16x32_bf16 v[96:99], v[178:181], v[194:197], v[96:99]
	v_mfma_f32_16x16x32_bf16 v[84:87], v[170:173], v[202:205], v[84:87]
	v_mfma_f32_16x16x32_bf16 v[80:83], v[178:181], v[202:205], v[80:83]
	v_mfma_f32_16x16x32_bf16 v[68:71], v[170:173], v[210:213], v[68:71]
	v_mfma_f32_16x16x32_bf16 v[64:67], v[178:181], v[210:213], v[64:67]
	v_mfma_f32_16x16x32_bf16 v[116:119], v[174:177], v[190:193], v[116:119]
	v_mfma_f32_16x16x32_bf16 v[112:115], v[182:185], v[190:193], v[112:115]
	v_mfma_f32_16x16x32_bf16 v[100:103], v[174:177], v[198:201], v[100:103]
	v_mfma_f32_16x16x32_bf16 v[96:99], v[182:185], v[198:201], v[96:99]
	v_mfma_f32_16x16x32_bf16 v[84:87], v[174:177], v[206:209], v[84:87]
	v_mfma_f32_16x16x32_bf16 v[80:83], v[182:185], v[206:209], v[80:83]
	v_mfma_f32_16x16x32_bf16 v[68:71], v[174:177], v[214:217], v[68:71]
	v_mfma_f32_16x16x32_bf16 v[64:67], v[182:185], v[214:217], v[64:67]
	s_setprio 0
	s_barrier
; #define PG8_STAGE(bufoff, gbase, voff) do { _Pragma("unroll") for (int _i = 0; _i < 2; ++_i) \
;         __builtin_amdgcn_global_load_lds((const unsigned*)((const char*)(gbase) + (voff)[_i]), (PG8_LAS unsigned*)(lds + (bufoff) + ldsw + _i * 8192), 16, 0, 0); } while (0)
; #define PG8_LDA(dst, b, h) do { _Pragma("unroll") for (int m = 0; m < 4; ++m) _Pragma("unroll") for (int k = 0; k < 2; ++k) dst[m][k] = *(const PG8_LAS bf16x8*)(lds + PG8_SA(b, h) + aoff + m * 2048 + k * 1024); } while (0)
; #define PG8_MMA(ai, bj, At, Bt) do { __builtin_amdgcn_s_setprio(1); _Pragma("unroll") for (int m = 0; m < 4; ++m) _Pragma("unroll") for (int n = 0; n < 2; ++n) _Pragma("unroll") for (int k = 0; k < 2; ++k) \
;         acc[ai][bj][m][n] = __builtin_amdgcn_mfma_f32_16x16x32_bf16(Bt[n][k], At[m][k], acc[ai][bj][m][n], 0, 0, 0); __builtin_amdgcn_s_setprio(0); } while (0)
; #define PG8_WAIT_V(n) asm volatile("s_waitcnt vmcnt(" #n ")" ::: "memory")
; #define PG8_WAIT_L(n) asm volatile("s_waitcnt lgkmcnt(" #n ")" ::: "memory")
; #define PG8_BAR __builtin_amdgcn_s_barrier()
; #define PG8_SCHED __builtin_amdgcn_sched_barrier(0)
; template <class Epi, class Sched, bool ALIGN_EPI = false, bool SP2 = false>
; __device__ __forceinline__ void gemm_phase(PG8_LAS unsigned char* lds, const Gemm g, const Sched& S, const Epi& E) {
;     ...
;             PG8_LDA(At, 1, 1); PG8_STAGE(PG8_SB(1, 0), b3, voffB); PG8_STAGE(PG8_SB(1, 1), b3 + hstepB, voffB); PG8_STAGE(PG8_SA(1, 0), a3, voffA);
;             PG8_WAIT_V(8); PG8_WAIT_L(0); PG8_BAR; if (whole) { PG8_MMA(1, 0, At, B0); PG8_MMA(1, 1, At, B1); } PG8_BAR; PG8_SCHED;
	s_add_i32 s17, s17, s53
	v_lshl_add_u64 v[218:219], v[218:219], 0, s[80:81]
	s_mov_b32 m0, s17
	ds_read_b128 v[186:189], v163 offset:49152
	ds_read_b128 v[190:193], v163 offset:50176
	ds_read_b128 v[194:197], v163 offset:51200
	ds_read_b128 v[198:201], v163 offset:52224
	ds_read_b128 v[202:205], v163 offset:53248
	ds_read_b128 v[206:209], v163 offset:54272
	ds_read_b128 v[210:213], v163 offset:55296
	ds_read_b128 v[214:217], v163 offset:56320
	global_load_lds_dwordx4 v[218:219], off
	s_add_i32 m0, s17, 0x2000
	s_add_u32 s18, s94, 0x40080
	v_lshl_add_u64 v[218:219], v[220:221], 0, s[80:81]
	s_addc_u32 s19, s95, 0
	s_add_i32 s17, s20, s53
	global_load_lds_dwordx4 v[218:219], off
	v_lshl_add_u64 v[218:219], s[18:19], 0, v[130:131]
	s_mov_b32 m0, s17
	s_nop 0
	global_load_lds_dwordx4 v[218:219], off
	v_lshl_add_u64 v[218:219], s[18:19], 0, v[134:135]
	s_add_i32 m0, s17, 0x2000
	s_nop 0
	global_load_lds_dwordx4 v[218:219], off
	v_lshl_add_u64 v[218:219], v[222:223], 0, s[80:81]
	s_mov_b32 m0, s57
	s_nop 0
	global_load_lds_dwordx4 v[218:219], off
	v_lshl_add_u64 v[218:219], v[224:225], 0, s[80:81]
	s_mov_b32 m0, s58
	s_nop 0
	global_load_lds_dwordx4 v[218:219], off
	s_waitcnt vmcnt(8)
	s_waitcnt lgkmcnt(0)
	s_barrier
	s_setprio 1
	s_waitcnt lgkmcnt(0)
	v_mfma_f32_16x16x32_bf16 v[60:63], v[148:151], v[186:189], v[60:63]
	v_mfma_f32_16x16x32_bf16 v[56:59], v[156:159], v[186:189], v[56:59]
	v_mfma_f32_16x16x32_bf16 v[44:47], v[148:151], v[194:197], v[44:47]
	v_mfma_f32_16x16x32_bf16 v[40:43], v[156:159], v[194:197], v[40:43]
	v_mfma_f32_16x16x32_bf16 v[28:31], v[148:151], v[202:205], v[28:31]
	v_mfma_f32_16x16x32_bf16 v[24:27], v[156:159], v[202:205], v[24:27]
	v_mfma_f32_16x16x32_bf16 v[12:15], v[148:151], v[210:213], v[12:15]
	v_mfma_f32_16x16x32_bf16 v[8:11], v[156:159], v[210:213], v[8:11]
	v_mfma_f32_16x16x32_bf16 v[60:63], v[152:155], v[190:193], v[60:63]
	v_mfma_f32_16x16x32_bf16 v[56:59], v[166:169], v[190:193], v[56:59]
	v_mfma_f32_16x16x32_bf16 v[44:47], v[152:155], v[198:201], v[44:47]
	v_mfma_f32_16x16x32_bf16 v[40:43], v[166:169], v[198:201], v[40:43]
	v_mfma_f32_16x16x32_bf16 v[28:31], v[152:155], v[206:209], v[28:31]
	v_mfma_f32_16x16x32_bf16 v[24:27], v[166:169], v[206:209], v[24:27]
	v_mfma_f32_16x16x32_bf16 v[12:15], v[152:155], v[214:217], v[12:15]
	v_mfma_f32_16x16x32_bf16 v[8:11], v[166:169], v[214:217], v[8:11]
	s_setprio 0
	s_setprio 1
	v_mfma_f32_16x16x32_bf16 v[52:55], v[170:173], v[186:189], v[52:55]
	v_mfma_f32_16x16x32_bf16 v[48:51], v[178:181], v[186:189], v[48:51]
	v_mfma_f32_16x16x32_bf16 v[36:39], v[170:173], v[194:197], v[36:39]
	v_mfma_f32_16x16x32_bf16 v[32:35], v[178:181], v[194:197], v[32:35]
	v_mfma_f32_16x16x32_bf16 v[20:23], v[170:173], v[202:205], v[20:23]
	v_mfma_f32_16x16x32_bf16 v[16:19], v[178:181], v[202:205], v[16:19]
	v_mfma_f32_16x16x32_bf16 v[4:7], v[170:173], v[210:213], v[4:7]
	v_mfma_f32_16x16x32_bf16 v[0:3], v[178:181], v[210:213], v[0:3]
	v_mfma_f32_16x16x32_bf16 v[52:55], v[174:177], v[190:193], v[52:55]
	v_mfma_f32_16x16x32_bf16 v[48:51], v[182:185], v[190:193], v[48:51]
	v_mfma_f32_16x16x32_bf16 v[36:39], v[174:177], v[198:201], v[36:39]
	v_mfma_f32_16x16x32_bf16 v[32:35], v[182:185], v[198:201], v[32:35]
	v_mfma_f32_16x16x32_bf16 v[20:23], v[174:177], v[206:209], v[20:23]
	v_mfma_f32_16x16x32_bf16 v[16:19], v[182:185], v[206:209], v[16:19]
	v_mfma_f32_16x16x32_bf16 v[4:7], v[174:177], v[214:217], v[4:7]
	v_mfma_f32_16x16x32_bf16 v[0:3], v[182:185], v[214:217], v[0:3]
	s_setprio 0
	s_barrier
	s_add_i32 s16, s16, 2
	s_add_u32 s96, s96, 0x100
	s_addc_u32 s97, s97, 0
	s_add_u32 s14, s14, 0x100
	s_addc_u32 s15, s15, 0
	s_cmp_gt_u32 s16, 13
	s_cbranch_scc0 .LBB0_105
	s_branch .Lpeel_exit_in0

;     __device__ __forceinline__ void operator()(const f32x4 (&acc)[2][2][4][2], const Unit& u, int wr, int wc, int fr, int fq) const {
;         const bool whole = u.qa < 0;
;         const int row0 = u.pm * BM + wr * 64 + fr + (u.qa > 0 ? HALF : 0), col0 = u.pn * BM + wc * 32 + 8 * fq + (u.qb > 0 ? HALF : 0);
;         float rsv[2][4];
; #pragma unroll
;         for (int ai = 0; ai < 2; ++ai)
; #pragma unroll
;             for (int m = 0; m < 4; ++m) rsv[ai][m] = ss[row0 + ai * HALF + m * 16];
; #pragma unroll
;         for (int ai = 0; ai < 2; ++ai)
; #pragma unroll
;             for (int m = 0; m < 4; ++m) rsv[ai][m] = __builtin_amdgcn_rsqf(rsv[ai][m] * (1.0f / 1024.0f) + RMS_EPS);
; #pragma unroll
;         for (int ai = 0; ai < 2; ++ai)
; #pragma unroll
;             for (int m = 0; m < 4; ++m) {
;                 if (ai == 1 && !whole) continue;
;                 const int row = row0 + ai * HALF + m * 16;
;                 const float rs = rsv[ai][m];
;                 float s1 = 0.f, s2 = 0.f;
;                 bf16_t* rowp = BLK ? O + ((size_t)u.pm * (ldc >> 6) + (size_t)(col0 >> 6)) * 16384 + (size_t)((col0 >> 5) & 1) * 8192 + (size_t)(row - u.pm * BM) * 32 + (col0 & 31) : O + (size_t)row * ldc + col0;
; #pragma unroll
;                 for (int bj = 0; bj < 2; ++bj) {
;                     if (bj == 1 && !whole) continue;
;                     f32x4 v0 = acc[ai][bj][m][0] * rs, v1 = acc[ai][bj][m][1] * rs;
;                     if (ACT == 1) {
; #pragma unroll
;                         for (int j = 0; j < 4; ++j) { const float a = fmaxf(v0[j], 0.f), b = fmaxf(v1[j], 0.f); v0[j] = a * a; v1[j] = b * b; }
;                     }
;                     u32x4 w; w.x = cvt_pk_bf16(v0[0], v0[1]); w.y = cvt_pk_bf16(v0[2], v0[3]); w.z = cvt_pk_bf16(v1[0], v1[1]); w.w = cvt_pk_bf16(v1[2], v1[3]);
;                     *(u32x4*)(rowp + (BLK ? bj * 2 * 16384 : bj * HALF)) = w;
;                     if (STATS) { s1 += (v0[0] + v0[1]) + (v0[2] + v0[3]) + (v1[0] + v1[1]) + (v1[2] + v1[3]);
;                         s2 += (v0[0] * v0[0] + v0[1] * v0[1]) + (v0[2] * v0[2] + v0[3] * v0[3]) + (v1[0] * v1[0] + v1[1] * v1[1]) + (v1[2] * v1[2] + v1[3] * v1[3]); }
;                 }
;                 if (STATS && u.pn >= stat_pn0) {
;                     s1 += __shfl_xor(s1, 16); s1 += __shfl_xor(s1, 32); s2 += __shfl_xor(s2, 16); s2 += __shfl_xor(s2, 32);
.Lpeel_exit_in1:
	s_and_b64 vcc, exec, s[54:55]
	s_cbranch_vccz .LBB0_748
	s_barrier
.LBB0_748:
	v_lshl_add_u32 v160, s64, 8, v162
	v_ashrrev_i32_e32 v161, 31, v160
	v_or_b32_e32 v158, 16, v160
	v_lshl_add_u64 v[144:145], v[160:161], 2, s[38:39]
	v_or_b32_e32 v156, 32, v160
	v_or_b32_e32 v154, 48, v160
	v_ashrrev_i32_e32 v159, 31, v158
	global_load_dword v177, v[144:145], off
	v_ashrrev_i32_e32 v157, 31, v156
	v_ashrrev_i32_e32 v155, 31, v154
	v_add_u32_e32 v152, 0x80, v160
	v_add_u32_e32 v150, 0x90, v160
	v_add_u32_e32 v146, 0xa0, v160
	v_add_u32_e32 v144, 0xb0, v160
	v_lshl_add_u64 v[148:149], v[158:159], 2, s[38:39]
	v_lshl_add_u64 v[170:171], v[156:157], 2, s[38:39]
	v_lshl_add_u64 v[172:173], v[154:155], 2, s[38:39]
	v_ashrrev_i32_e32 v153, 31, v152
	v_ashrrev_i32_e32 v151, 31, v150
	v_ashrrev_i32_e32 v147, 31, v146
	v_ashrrev_i32_e32 v145, 31, v144
	v_lshl_add_u64 v[178:179], v[152:153], 2, s[38:39]
	v_lshl_add_u64 v[180:181], v[150:151], 2, s[38:39]
	v_lshl_add_u64 v[182:183], v[146:147], 2, s[38:39]
	v_lshl_add_u64 v[184:185], v[144:145], 2, s[38:39]
	global_load_dword v176, v[148:149], off
	global_load_dword v175, v[170:171], off
	global_load_dword v174, v[172:173], off
	s_nop 0
	global_load_dword v173, v[178:179], off
	global_load_dword v172, v[180:181], off
	global_load_dword v171, v[182:183], off
	global_load_dword v170, v[184:185], off
	v_lshl_or_b32 v148, s0, 8, v164
	v_mov_b64_e32 v[178:179], s[34:35]
	s_cmp_gt_i32 s0, 3
	v_ashrrev_i32_e32 v149, 31, v148
	v_mad_i64_i32 v[178:179], s[6:7], v160, s93, v[178:179]
	s_cselect_b64 s[6:7], -1, 0
	v_lshl_add_u64 v[182:183], v[148:149], 1, v[178:179]
	s_cmp_lt_i32 s0, 4
	s_waitcnt vmcnt(0)
	v_fmamk_f32 v177, v177, 0x3a800000, v168
	v_rsq_f32_e32 v180, v177
	s_nop 0
	v_pk_mul_f32 v[126:127], v[126:127], v[180:181] op_sel_hi:[1,0]
	v_pk_mul_f32 v[124:125], v[124:125], v[180:181] op_sel_hi:[1,0]
	v_pk_mul_f32 v[122:123], v[122:123], v[180:181] op_sel_hi:[1,0]
	v_pk_mul_f32 v[120:121], v[120:121], v[180:181] op_sel_hi:[1,0]
	v_pk_mul_f32 v[118:119], v[118:119], v[180:181] op_sel_hi:[1,0]
	v_pk_mul_f32 v[116:117], v[116:117], v[180:181] op_sel_hi:[1,0]
	v_pk_mul_f32 v[114:115], v[114:115], v[180:181] op_sel_hi:[1,0]
	v_pk_mul_f32 v[112:113], v[112:113], v[180:181] op_sel_hi:[1,0]
	v_cvt_pk_bf16_f32 v178, v124, v125
	v_cvt_pk_bf16_f32 v179, v126, v127
	v_cvt_pk_bf16_f32 v180, v120, v121
	v_cvt_pk_bf16_f32 v181, v122, v123
	global_store_dwordx4 v[182:183], v[178:181], off
	s_nop 1
	v_cvt_pk_bf16_f32 v178, v116, v117
	v_cvt_pk_bf16_f32 v179, v118, v119
	v_cvt_pk_bf16_f32 v180, v112, v113
	v_cvt_pk_bf16_f32 v181, v114, v115
	global_store_dwordx4 v[182:183], v[178:181], off offset:256
	s_cbranch_scc1 .LBB0_752
	s_nop 0
	v_mul_f32_e32 v178, v125, v125
	v_mul_f32_e32 v179, v127, v127
	v_fmac_f32_e32 v178, v124, v124
	v_fmac_f32_e32 v179, v126, v126
	v_add_f32_e32 v178, v178, v179
	v_mul_f32_e32 v179, v121, v121
	v_mul_f32_e32 v177, v123, v123
	v_fmac_f32_e32 v179, v120, v120
	v_fmac_f32_e32 v177, v122, v122
	v_add_f32_e32 v178, v179, v178
	v_add_f32_e32 v177, v177, v178
	v_mul_f32_e32 v178, v115, v115
	v_mul_f32_e32 v179, v117, v117
	v_mul_f32_e32 v180, v119, v119
	v_fmac_f32_e32 v178, v114, v114
	v_fmac_f32_e32 v179, v116, v116
	v_fmac_f32_e32 v180, v118, v118
	v_add_f32_e32 v114, v114, v115
	v_add_f32_e32 v115, v116, v117
	v_add_f32_e32 v116, v118, v119
	v_add_f32_e32 v179, v179, v180
	v_mul_f32_e32 v180, v113, v113
	v_add_f32_e32 v122, v122, v123
	v_add_f32_e32 v123, v124, v125
	v_add_f32_e32 v124, v126, v127
	v_add_f32_e32 v115, v115, v116
	v_add_f32_e32 v113, v112, v113
	v_add_f32_e32 v123, v123, v124
	v_add_f32_e32 v120, v120, v121
	v_add_f32_e32 v113, v113, v115
	v_and_b32_e32 v115, 64, v169
	v_add_f32_e32 v120, v120, v123
	v_add_f32_e32 v113, v114, v113
	v_xor_b32_e32 v114, 16, v169
	v_add_u32_e32 v115, 64, v115
	v_add_f32_e32 v120, v122, v120
	v_cmp_lt_i32_e32 vcc, v114, v115
	v_add_f32_e32 v120, 0, v120
	v_add_f32_e32 v113, v113, v120
	v_cndmask_b32_e32 v114, v169, v114, vcc
	v_lshlrev_b32_e32 v114, 2, v114
	v_fmac_f32_e32 v180, v112, v112
	ds_bpermute_b32 v116, v114, v113
	v_add_f32_e32 v112, v180, v179
	v_add_f32_e32 v112, v178, v112
	v_add_f32_e32 v117, v177, v112
	ds_bpermute_b32 v114, v114, v117
	s_waitcnt lgkmcnt(1)
	v_add_f32_e32 v112, v113, v116
	v_xor_b32_e32 v113, 32, v169
	v_cmp_lt_i32_e32 vcc, v113, v115
	s_waitcnt lgkmcnt(0)
	v_add_f32_e32 v114, v117, v114
	v_cndmask_b32_e32 v113, v169, v113, vcc
	v_lshlrev_b32_e32 v115, 2, v113
	ds_bpermute_b32 v113, v115, v112
	ds_bpermute_b32 v115, v115, v114
	s_and_saveexec_b64 s[0:1], s[2:3]
	s_cbranch_execz .LBB0_751
	s_waitcnt lgkmcnt(1)
	v_add_f32_e32 v117, v112, v113
	v_lshlrev_b64 v[112:113], 2, v[160:161]
	s_waitcnt lgkmcnt(0)
	v_add_f32_e32 v116, v114, v115
	v_lshl_add_u64 v[114:115], s[46:47], 0, v[112:113]
	v_lshl_add_u64 v[112:113], s[50:51], 0, v[112:113]
	global_atomic_add_f32 v[114:115], v117, off
	global_atomic_add_f32 v[112:113], v116, off
